# adds hand-written q/k RMS-norm+rotary epilogue with block-wise double-buffered gain/rope loads (phase 2 tiles nt<=4)
# baseline (speedup 1.0000x reference)
.Lepi2_orig:
	s_cmp_gt_i32 s36, 4
	s_cbranch_scc1 .Lepi2_hip
	s_cmp_eq_u32 s36, 4
	s_cselect_b32 s58, s72, s70
	s_cselect_b32 s59, s73, s71
	s_lshl_b32 s12, s34, 8
	s_and_b32 s12, s12, 0x700
	v_lshrrev_b32_e32 v229, 1, v208
	v_and_b32_e32 v229, 0xffffffc0, v229
	v_and_b32_e32 v230, 31, v208
	v_or_b32_e32 v229, v229, v230
	v_mul_u32_u24_e32 v204, 0x210, v229
	v_lshlrev_b32_e32 v230, 2, v208
	v_and_b32_e32 v230, 0x100, v230
	v_add_u32_e32 v204, v204, v230
	v_lshrrev_b32_e32 v230, 2, v208
	v_and_b32_e32 v230, 8, v230
	v_add_u32_e32 v204, v204, v230
	v_lshlrev_b32_e32 v170, 1, v230
	v_lshlrev_b32_e32 v230, 2, v230
	v_add_u32_e32 v200, s12, v229
	v_and_b32_e32 v201, 63, v200
	v_lshrrev_b32_e32 v200, 6, v200
	v_lshl_add_u32 v200, v200, 8, v230
	v_lshl_add_u32 v201, v201, 8, v230
	v_add_u32_e32 v202, s12, v229
	v_add_u32_e32 v202, 32, v202
	v_and_b32_e32 v203, 63, v202
	v_lshrrev_b32_e32 v202, 6, v202
	v_lshl_add_u32 v202, v202, 8, v230
	v_lshl_add_u32 v203, v203, 8, v230
	v_lshrrev_b32_e32 v229, 5, v208
	v_and_b32_e32 v207, 31, v208
	v_lshlrev_b32_e32 v207, 4, v207
	v_mul_u32_u24_e32 v205, 0x210, v229
	v_add_u32_e32 v205, v205, v207
	v_add_u32_e32 v206, 0x10800, v205
	v_pk_mul_f32 v[180:181], v[112:113], v[112:113]
	v_pk_fma_f32 v[180:181], v[114:115], v[114:115], v[180:181]
	v_pk_fma_f32 v[180:181], v[116:117], v[116:117], v[180:181]
	v_pk_fma_f32 v[180:181], v[118:119], v[118:119], v[180:181]
	v_pk_fma_f32 v[180:181], v[120:121], v[120:121], v[180:181]
	v_pk_fma_f32 v[180:181], v[122:123], v[122:123], v[180:181]
	v_pk_fma_f32 v[180:181], v[124:125], v[124:125], v[180:181]
	v_pk_fma_f32 v[180:181], v[126:127], v[126:127], v[180:181]
	v_pk_fma_f32 v[180:181], v[80:81], v[80:81], v[180:181]
	v_pk_fma_f32 v[180:181], v[82:83], v[82:83], v[180:181]
	v_pk_fma_f32 v[180:181], v[84:85], v[84:85], v[180:181]
	v_pk_fma_f32 v[180:181], v[86:87], v[86:87], v[180:181]
	v_pk_fma_f32 v[180:181], v[88:89], v[88:89], v[180:181]
	v_pk_fma_f32 v[180:181], v[90:91], v[90:91], v[180:181]
	v_pk_fma_f32 v[180:181], v[92:93], v[92:93], v[180:181]
	v_pk_fma_f32 v[180:181], v[94:95], v[94:95], v[180:181]
	v_pk_fma_f32 v[180:181], v[96:97], v[96:97], v[180:181]
	v_pk_fma_f32 v[180:181], v[98:99], v[98:99], v[180:181]
	v_pk_fma_f32 v[180:181], v[100:101], v[100:101], v[180:181]
	v_pk_fma_f32 v[180:181], v[102:103], v[102:103], v[180:181]
	v_pk_fma_f32 v[180:181], v[104:105], v[104:105], v[180:181]
	v_pk_fma_f32 v[180:181], v[106:107], v[106:107], v[180:181]
	v_pk_fma_f32 v[180:181], v[108:109], v[108:109], v[180:181]
	v_pk_fma_f32 v[180:181], v[110:111], v[110:111], v[180:181]
	v_pk_fma_f32 v[180:181], v[64:65], v[64:65], v[180:181]
	v_pk_fma_f32 v[180:181], v[66:67], v[66:67], v[180:181]
	v_pk_fma_f32 v[180:181], v[68:69], v[68:69], v[180:181]
	v_pk_fma_f32 v[180:181], v[70:71], v[70:71], v[180:181]
	v_pk_fma_f32 v[180:181], v[72:73], v[72:73], v[180:181]
	v_pk_fma_f32 v[180:181], v[74:75], v[74:75], v[180:181]
	v_pk_fma_f32 v[180:181], v[76:77], v[76:77], v[180:181]
	v_pk_fma_f32 v[180:181], v[78:79], v[78:79], v[180:181]
	v_add_f32_e32 v180, v180, v181
	v_mov_b32_e32 v181, v180
	s_nop 1
	v_permlane32_swap_b32_e32 v180, v181
	s_nop 1
	v_add_f32_e32 v180, v180, v181
	v_mov_b32_e32 v181, 0x358637bd
	v_fmac_f32_e32 v181, 0x3c000000, v180
	v_rsq_f32_e32 v196, v181
	s_nop 0
	v_mov_b32_e32 v197, v196
	v_pk_mul_f32 v[180:181], v[48:49], v[48:49]
	v_pk_fma_f32 v[180:181], v[50:51], v[50:51], v[180:181]
	v_pk_fma_f32 v[180:181], v[52:53], v[52:53], v[180:181]
	v_pk_fma_f32 v[180:181], v[54:55], v[54:55], v[180:181]
	v_pk_fma_f32 v[180:181], v[56:57], v[56:57], v[180:181]
	v_pk_fma_f32 v[180:181], v[58:59], v[58:59], v[180:181]
	v_pk_fma_f32 v[180:181], v[60:61], v[60:61], v[180:181]
	v_pk_fma_f32 v[180:181], v[62:63], v[62:63], v[180:181]
	v_pk_fma_f32 v[180:181], v[16:17], v[16:17], v[180:181]
	v_pk_fma_f32 v[180:181], v[18:19], v[18:19], v[180:181]
	v_pk_fma_f32 v[180:181], v[20:21], v[20:21], v[180:181]
	v_pk_fma_f32 v[180:181], v[22:23], v[22:23], v[180:181]
	v_pk_fma_f32 v[180:181], v[24:25], v[24:25], v[180:181]
	v_pk_fma_f32 v[180:181], v[26:27], v[26:27], v[180:181]
	v_pk_fma_f32 v[180:181], v[28:29], v[28:29], v[180:181]
	v_pk_fma_f32 v[180:181], v[30:31], v[30:31], v[180:181]
	v_pk_fma_f32 v[180:181], v[32:33], v[32:33], v[180:181]
	v_pk_fma_f32 v[180:181], v[34:35], v[34:35], v[180:181]
	v_pk_fma_f32 v[180:181], v[36:37], v[36:37], v[180:181]
	v_pk_fma_f32 v[180:181], v[38:39], v[38:39], v[180:181]
	v_pk_fma_f32 v[180:181], v[40:41], v[40:41], v[180:181]
	v_pk_fma_f32 v[180:181], v[42:43], v[42:43], v[180:181]
	v_pk_fma_f32 v[180:181], v[44:45], v[44:45], v[180:181]
	v_pk_fma_f32 v[180:181], v[46:47], v[46:47], v[180:181]
	v_pk_fma_f32 v[180:181], v[0:1], v[0:1], v[180:181]
	v_pk_fma_f32 v[180:181], v[2:3], v[2:3], v[180:181]
	v_pk_fma_f32 v[180:181], v[4:5], v[4:5], v[180:181]
	v_pk_fma_f32 v[180:181], v[6:7], v[6:7], v[180:181]
	v_pk_fma_f32 v[180:181], v[8:9], v[8:9], v[180:181]
	v_pk_fma_f32 v[180:181], v[10:11], v[10:11], v[180:181]
	v_pk_fma_f32 v[180:181], v[12:13], v[12:13], v[180:181]
	v_pk_fma_f32 v[180:181], v[14:15], v[14:15], v[180:181]
	v_add_f32_e32 v180, v180, v181
	v_mov_b32_e32 v181, v180
	s_nop 1
	v_permlane32_swap_b32_e32 v180, v181
	s_nop 1
	v_add_f32_e32 v180, v180, v181
	v_mov_b32_e32 v181, 0x358637bd
	v_fmac_f32_e32 v181, 0x3c000000, v180
	v_rsq_f32_e32 v198, v181
	s_nop 0
	v_mov_b32_e32 v199, v198
	s_cmpk_gt_i32 s42, 0xaff
	s_cbranch_scc1 .Lqk2_ctx
	global_load_dwordx4 v[128:131], v170, s[58:59] offset:0
	global_load_dwordx4 v[132:135], v170, s[58:59] offset:256
	global_load_dwordx4 v[144:147], v200, s[8:9] offset:0
	global_load_dwordx4 v[148:151], v200, s[8:9] offset:16
	global_load_dwordx4 v[152:155], v202, s[8:9] offset:0
	global_load_dwordx4 v[156:159], v202, s[8:9] offset:16
	global_load_dwordx4 v[136:139], v170, s[58:59] offset:32
	global_load_dwordx4 v[140:143], v170, s[58:59] offset:288
	global_load_dwordx4 v[160:163], v200, s[8:9] offset:64
	global_load_dwordx4 v[164:167], v200, s[8:9] offset:80
	global_load_dwordx4 v[172:175], v202, s[8:9] offset:64
	global_load_dwordx4 v[176:179], v202, s[8:9] offset:80
	s_waitcnt vmcnt(6)
	v_pk_mul_f32 v[180:181], v[112:113], v[196:197]
	v_pk_mul_f32 v[184:185], v[96:97], v[196:197]
	v_pk_mul_f32 v[182:183], v[114:115], v[196:197]
	v_pk_mul_f32 v[186:187], v[98:99], v[196:197]
	v_pk_mul_f32 v[180:181], v[180:181], v[128:129]
	v_pk_mul_f32 v[184:185], v[184:185], v[132:133]
	v_pk_mul_f32 v[182:183], v[182:183], v[130:131]
	v_pk_mul_f32 v[186:187], v[186:187], v[134:135]
	v_mul_f32_e32 v188, v184, v145
	v_mul_f32_e32 v192, v180, v145
	v_mul_f32_e32 v189, v185, v147
	v_mul_f32_e32 v193, v181, v147
	v_mul_f32_e32 v190, v186, v149
	v_mul_f32_e32 v194, v182, v149
	v_mul_f32_e32 v191, v187, v151
	v_mul_f32_e32 v195, v183, v151
	v_fma_f32 v188, v180, v144, -v188
	v_fma_f32 v192, v184, v144, v192
	v_fma_f32 v189, v181, v146, -v189
	v_fma_f32 v193, v185, v146, v193
	v_fma_f32 v190, v182, v148, -v190
	v_fma_f32 v194, v186, v148, v194
	v_fma_f32 v191, v183, v150, -v191
	v_fma_f32 v195, v187, v150, v195
	v_cvt_pk_bf16_f32 v188, v188, v189
	v_cvt_pk_bf16_f32 v189, v190, v191
	v_cvt_pk_bf16_f32 v190, v192, v193
	v_cvt_pk_bf16_f32 v191, v194, v195
	ds_write_b64 v204, v[188:189] offset:0
	ds_write_b64 v204, v[190:191] offset:128
	v_pk_mul_f32 v[180:181], v[48:49], v[198:199]
	v_pk_mul_f32 v[184:185], v[32:33], v[198:199]
	v_pk_mul_f32 v[182:183], v[50:51], v[198:199]
	v_pk_mul_f32 v[186:187], v[34:35], v[198:199]
	v_pk_mul_f32 v[180:181], v[180:181], v[128:129]
	v_pk_mul_f32 v[184:185], v[184:185], v[132:133]
	v_pk_mul_f32 v[182:183], v[182:183], v[130:131]
	v_pk_mul_f32 v[186:187], v[186:187], v[134:135]
	v_mul_f32_e32 v188, v184, v153
	v_mul_f32_e32 v192, v180, v153
	v_mul_f32_e32 v189, v185, v155
	v_mul_f32_e32 v193, v181, v155
	v_mul_f32_e32 v190, v186, v157
	v_mul_f32_e32 v194, v182, v157
	v_mul_f32_e32 v191, v187, v159
	v_mul_f32_e32 v195, v183, v159
	v_fma_f32 v188, v180, v152, -v188
	v_fma_f32 v192, v184, v152, v192
	v_fma_f32 v189, v181, v154, -v189
	v_fma_f32 v193, v185, v154, v193
	v_fma_f32 v190, v182, v156, -v190
	v_fma_f32 v194, v186, v156, v194
	v_fma_f32 v191, v183, v158, -v191
	v_fma_f32 v195, v187, v158, v195
	v_cvt_pk_bf16_f32 v188, v188, v189
	v_cvt_pk_bf16_f32 v189, v190, v191
	v_cvt_pk_bf16_f32 v190, v192, v193
	v_cvt_pk_bf16_f32 v191, v194, v195
	ds_write_b64 v204, v[188:189] offset:16896
	ds_write_b64 v204, v[190:191] offset:17024
	global_load_dwordx4 v[128:131], v170, s[58:59] offset:64
	global_load_dwordx4 v[132:135], v170, s[58:59] offset:320
	global_load_dwordx4 v[144:147], v200, s[8:9] offset:128
	global_load_dwordx4 v[148:151], v200, s[8:9] offset:144
	global_load_dwordx4 v[152:155], v202, s[8:9] offset:128
	global_load_dwordx4 v[156:159], v202, s[8:9] offset:144
	s_waitcnt vmcnt(6)
	v_pk_mul_f32 v[180:181], v[116:117], v[196:197]
	v_pk_mul_f32 v[184:185], v[100:101], v[196:197]
	v_pk_mul_f32 v[182:183], v[118:119], v[196:197]
	v_pk_mul_f32 v[186:187], v[102:103], v[196:197]
	v_pk_mul_f32 v[180:181], v[180:181], v[136:137]
	v_pk_mul_f32 v[184:185], v[184:185], v[140:141]
	v_pk_mul_f32 v[182:183], v[182:183], v[138:139]
	v_pk_mul_f32 v[186:187], v[186:187], v[142:143]
	v_mul_f32_e32 v188, v184, v161
	v_mul_f32_e32 v192, v180, v161
	v_mul_f32_e32 v189, v185, v163
	v_mul_f32_e32 v193, v181, v163
	v_mul_f32_e32 v190, v186, v165
	v_mul_f32_e32 v194, v182, v165
	v_mul_f32_e32 v191, v187, v167
	v_mul_f32_e32 v195, v183, v167
	v_fma_f32 v188, v180, v160, -v188
	v_fma_f32 v192, v184, v160, v192
	v_fma_f32 v189, v181, v162, -v189
	v_fma_f32 v193, v185, v162, v193
	v_fma_f32 v190, v182, v164, -v190
	v_fma_f32 v194, v186, v164, v194
	v_fma_f32 v191, v183, v166, -v191
	v_fma_f32 v195, v187, v166, v195
	v_cvt_pk_bf16_f32 v188, v188, v189
	v_cvt_pk_bf16_f32 v189, v190, v191
	v_cvt_pk_bf16_f32 v190, v192, v193
	v_cvt_pk_bf16_f32 v191, v194, v195
	ds_write_b64 v204, v[188:189] offset:16
	ds_write_b64 v204, v[190:191] offset:144
	v_pk_mul_f32 v[180:181], v[52:53], v[198:199]
	v_pk_mul_f32 v[184:185], v[36:37], v[198:199]
	v_pk_mul_f32 v[182:183], v[54:55], v[198:199]
	v_pk_mul_f32 v[186:187], v[38:39], v[198:199]
	v_pk_mul_f32 v[180:181], v[180:181], v[136:137]
	v_pk_mul_f32 v[184:185], v[184:185], v[140:141]
	v_pk_mul_f32 v[182:183], v[182:183], v[138:139]
	v_pk_mul_f32 v[186:187], v[186:187], v[142:143]
	v_mul_f32_e32 v188, v184, v173
	v_mul_f32_e32 v192, v180, v173
	v_mul_f32_e32 v189, v185, v175
	v_mul_f32_e32 v193, v181, v175
	v_mul_f32_e32 v190, v186, v177
	v_mul_f32_e32 v194, v182, v177
	v_mul_f32_e32 v191, v187, v179
	v_mul_f32_e32 v195, v183, v179
	v_fma_f32 v188, v180, v172, -v188
	v_fma_f32 v192, v184, v172, v192
	v_fma_f32 v189, v181, v174, -v189
	v_fma_f32 v193, v185, v174, v193
	v_fma_f32 v190, v182, v176, -v190
	v_fma_f32 v194, v186, v176, v194
	v_fma_f32 v191, v183, v178, -v191
	v_fma_f32 v195, v187, v178, v195
	v_cvt_pk_bf16_f32 v188, v188, v189
	v_cvt_pk_bf16_f32 v189, v190, v191
	v_cvt_pk_bf16_f32 v190, v192, v193
	v_cvt_pk_bf16_f32 v191, v194, v195
	ds_write_b64 v204, v[188:189] offset:16912
	ds_write_b64 v204, v[190:191] offset:17040
	global_load_dwordx4 v[136:139], v170, s[58:59] offset:96
	global_load_dwordx4 v[140:143], v170, s[58:59] offset:352
	global_load_dwordx4 v[160:163], v200, s[8:9] offset:192
	global_load_dwordx4 v[164:167], v200, s[8:9] offset:208
	global_load_dwordx4 v[172:175], v202, s[8:9] offset:192
	global_load_dwordx4 v[176:179], v202, s[8:9] offset:208
	s_waitcnt vmcnt(6)
	v_pk_mul_f32 v[180:181], v[120:121], v[196:197]
	v_pk_mul_f32 v[184:185], v[104:105], v[196:197]
	v_pk_mul_f32 v[182:183], v[122:123], v[196:197]
	v_pk_mul_f32 v[186:187], v[106:107], v[196:197]
	v_pk_mul_f32 v[180:181], v[180:181], v[128:129]
	v_pk_mul_f32 v[184:185], v[184:185], v[132:133]
	v_pk_mul_f32 v[182:183], v[182:183], v[130:131]
	v_pk_mul_f32 v[186:187], v[186:187], v[134:135]
	v_mul_f32_e32 v188, v184, v145
	v_mul_f32_e32 v192, v180, v145
	v_mul_f32_e32 v189, v185, v147
	v_mul_f32_e32 v193, v181, v147
	v_mul_f32_e32 v190, v186, v149
	v_mul_f32_e32 v194, v182, v149
	v_mul_f32_e32 v191, v187, v151
	v_mul_f32_e32 v195, v183, v151
	v_fma_f32 v188, v180, v144, -v188
	v_fma_f32 v192, v184, v144, v192
	v_fma_f32 v189, v181, v146, -v189
	v_fma_f32 v193, v185, v146, v193
	v_fma_f32 v190, v182, v148, -v190
	v_fma_f32 v194, v186, v148, v194
	v_fma_f32 v191, v183, v150, -v191
	v_fma_f32 v195, v187, v150, v195
	v_cvt_pk_bf16_f32 v188, v188, v189
	v_cvt_pk_bf16_f32 v189, v190, v191
	v_cvt_pk_bf16_f32 v190, v192, v193
	v_cvt_pk_bf16_f32 v191, v194, v195
	ds_write_b64 v204, v[188:189] offset:32
	ds_write_b64 v204, v[190:191] offset:160
	v_pk_mul_f32 v[180:181], v[56:57], v[198:199]
	v_pk_mul_f32 v[184:185], v[40:41], v[198:199]
	v_pk_mul_f32 v[182:183], v[58:59], v[198:199]
	v_pk_mul_f32 v[186:187], v[42:43], v[198:199]
	v_pk_mul_f32 v[180:181], v[180:181], v[128:129]
	v_pk_mul_f32 v[184:185], v[184:185], v[132:133]
	v_pk_mul_f32 v[182:183], v[182:183], v[130:131]
	v_pk_mul_f32 v[186:187], v[186:187], v[134:135]
	v_mul_f32_e32 v188, v184, v153
	v_mul_f32_e32 v192, v180, v153
	v_mul_f32_e32 v189, v185, v155
	v_mul_f32_e32 v193, v181, v155
	v_mul_f32_e32 v190, v186, v157
	v_mul_f32_e32 v194, v182, v157
	v_mul_f32_e32 v191, v187, v159
	v_mul_f32_e32 v195, v183, v159
	v_fma_f32 v188, v180, v152, -v188
	v_fma_f32 v192, v184, v152, v192
	v_fma_f32 v189, v181, v154, -v189
	v_fma_f32 v193, v185, v154, v193
	v_fma_f32 v190, v182, v156, -v190
	v_fma_f32 v194, v186, v156, v194
	v_fma_f32 v191, v183, v158, -v191
	v_fma_f32 v195, v187, v158, v195
	v_cvt_pk_bf16_f32 v188, v188, v189
	v_cvt_pk_bf16_f32 v189, v190, v191
	v_cvt_pk_bf16_f32 v190, v192, v193
	v_cvt_pk_bf16_f32 v191, v194, v195
	ds_write_b64 v204, v[188:189] offset:16928
	ds_write_b64 v204, v[190:191] offset:17056
	global_load_dwordx4 v[128:131], v170, s[58:59] offset:128
	global_load_dwordx4 v[132:135], v170, s[58:59] offset:384
	global_load_dwordx4 v[144:147], v201, s[8:9] offset:0
	global_load_dwordx4 v[148:151], v201, s[8:9] offset:16
	global_load_dwordx4 v[152:155], v203, s[8:9] offset:0
	global_load_dwordx4 v[156:159], v203, s[8:9] offset:16
	s_waitcnt vmcnt(6)
	v_pk_mul_f32 v[180:181], v[124:125], v[196:197]
	v_pk_mul_f32 v[184:185], v[108:109], v[196:197]
	v_pk_mul_f32 v[182:183], v[126:127], v[196:197]
	v_pk_mul_f32 v[186:187], v[110:111], v[196:197]
	v_pk_mul_f32 v[180:181], v[180:181], v[136:137]
	v_pk_mul_f32 v[184:185], v[184:185], v[140:141]
	v_pk_mul_f32 v[182:183], v[182:183], v[138:139]
	v_pk_mul_f32 v[186:187], v[186:187], v[142:143]
	v_mul_f32_e32 v188, v184, v161
	v_mul_f32_e32 v192, v180, v161
	v_mul_f32_e32 v189, v185, v163
	v_mul_f32_e32 v193, v181, v163
	v_mul_f32_e32 v190, v186, v165
	v_mul_f32_e32 v194, v182, v165
	v_mul_f32_e32 v191, v187, v167
	v_mul_f32_e32 v195, v183, v167
	v_fma_f32 v188, v180, v160, -v188
	v_fma_f32 v192, v184, v160, v192
	v_fma_f32 v189, v181, v162, -v189
	v_fma_f32 v193, v185, v162, v193
	v_fma_f32 v190, v182, v164, -v190
	v_fma_f32 v194, v186, v164, v194
	v_fma_f32 v191, v183, v166, -v191
	v_fma_f32 v195, v187, v166, v195
	v_cvt_pk_bf16_f32 v188, v188, v189
	v_cvt_pk_bf16_f32 v189, v190, v191
	v_cvt_pk_bf16_f32 v190, v192, v193
	v_cvt_pk_bf16_f32 v191, v194, v195
	ds_write_b64 v204, v[188:189] offset:48
	ds_write_b64 v204, v[190:191] offset:176
	v_pk_mul_f32 v[180:181], v[60:61], v[198:199]
	v_pk_mul_f32 v[184:185], v[44:45], v[198:199]
	v_pk_mul_f32 v[182:183], v[62:63], v[198:199]
	v_pk_mul_f32 v[186:187], v[46:47], v[198:199]
	v_pk_mul_f32 v[180:181], v[180:181], v[136:137]
	v_pk_mul_f32 v[184:185], v[184:185], v[140:141]
	v_pk_mul_f32 v[182:183], v[182:183], v[138:139]
	v_pk_mul_f32 v[186:187], v[186:187], v[142:143]
	v_mul_f32_e32 v188, v184, v173
	v_mul_f32_e32 v192, v180, v173
	v_mul_f32_e32 v189, v185, v175
	v_mul_f32_e32 v193, v181, v175
	v_mul_f32_e32 v190, v186, v177
	v_mul_f32_e32 v194, v182, v177
	v_mul_f32_e32 v191, v187, v179
	v_mul_f32_e32 v195, v183, v179
	v_fma_f32 v188, v180, v172, -v188
	v_fma_f32 v192, v184, v172, v192
	v_fma_f32 v189, v181, v174, -v189
	v_fma_f32 v193, v185, v174, v193
	v_fma_f32 v190, v182, v176, -v190
	v_fma_f32 v194, v186, v176, v194
	v_fma_f32 v191, v183, v178, -v191
	v_fma_f32 v195, v187, v178, v195
	v_cvt_pk_bf16_f32 v188, v188, v189
	v_cvt_pk_bf16_f32 v189, v190, v191
	v_cvt_pk_bf16_f32 v190, v192, v193
	v_cvt_pk_bf16_f32 v191, v194, v195
	ds_write_b64 v204, v[188:189] offset:16944
	ds_write_b64 v204, v[190:191] offset:17072
	global_load_dwordx4 v[136:139], v170, s[58:59] offset:160
	global_load_dwordx4 v[140:143], v170, s[58:59] offset:416
	global_load_dwordx4 v[160:163], v201, s[8:9] offset:64
	global_load_dwordx4 v[164:167], v201, s[8:9] offset:80
	global_load_dwordx4 v[172:175], v203, s[8:9] offset:64
	global_load_dwordx4 v[176:179], v203, s[8:9] offset:80
	s_waitcnt vmcnt(6)
	v_pk_mul_f32 v[180:181], v[80:81], v[196:197]
	v_pk_mul_f32 v[184:185], v[64:65], v[196:197]
	v_pk_mul_f32 v[182:183], v[82:83], v[196:197]
	v_pk_mul_f32 v[186:187], v[66:67], v[196:197]
	v_pk_mul_f32 v[180:181], v[180:181], v[128:129]
	v_pk_mul_f32 v[184:185], v[184:185], v[132:133]
	v_pk_mul_f32 v[182:183], v[182:183], v[130:131]
	v_pk_mul_f32 v[186:187], v[186:187], v[134:135]
	v_mul_f32_e32 v188, v184, v145
	v_mul_f32_e32 v192, v180, v145
	v_mul_f32_e32 v189, v185, v147
	v_mul_f32_e32 v193, v181, v147
	v_mul_f32_e32 v190, v186, v149
	v_mul_f32_e32 v194, v182, v149
	v_mul_f32_e32 v191, v187, v151
	v_mul_f32_e32 v195, v183, v151
	v_fma_f32 v188, v180, v144, -v188
	v_fma_f32 v192, v184, v144, v192
	v_fma_f32 v189, v181, v146, -v189
	v_fma_f32 v193, v185, v146, v193
	v_fma_f32 v190, v182, v148, -v190
	v_fma_f32 v194, v186, v148, v194
	v_fma_f32 v191, v183, v150, -v191
	v_fma_f32 v195, v187, v150, v195
	v_cvt_pk_bf16_f32 v188, v188, v189
	v_cvt_pk_bf16_f32 v189, v190, v191
	v_cvt_pk_bf16_f32 v190, v192, v193
	v_cvt_pk_bf16_f32 v191, v194, v195
	ds_write_b64 v204, v[188:189] offset:64
	ds_write_b64 v204, v[190:191] offset:192
	v_pk_mul_f32 v[180:181], v[16:17], v[198:199]
	v_pk_mul_f32 v[184:185], v[0:1], v[198:199]
	v_pk_mul_f32 v[182:183], v[18:19], v[198:199]
	v_pk_mul_f32 v[186:187], v[2:3], v[198:199]
	v_pk_mul_f32 v[180:181], v[180:181], v[128:129]
	v_pk_mul_f32 v[184:185], v[184:185], v[132:133]
	v_pk_mul_f32 v[182:183], v[182:183], v[130:131]
	v_pk_mul_f32 v[186:187], v[186:187], v[134:135]
	v_mul_f32_e32 v188, v184, v153
	v_mul_f32_e32 v192, v180, v153
	v_mul_f32_e32 v189, v185, v155
	v_mul_f32_e32 v193, v181, v155
	v_mul_f32_e32 v190, v186, v157
	v_mul_f32_e32 v194, v182, v157
	v_mul_f32_e32 v191, v187, v159
	v_mul_f32_e32 v195, v183, v159
	v_fma_f32 v188, v180, v152, -v188
	v_fma_f32 v192, v184, v152, v192
	v_fma_f32 v189, v181, v154, -v189
	v_fma_f32 v193, v185, v154, v193
	v_fma_f32 v190, v182, v156, -v190
	v_fma_f32 v194, v186, v156, v194
	v_fma_f32 v191, v183, v158, -v191
	v_fma_f32 v195, v187, v158, v195
	v_cvt_pk_bf16_f32 v188, v188, v189
	v_cvt_pk_bf16_f32 v189, v190, v191
	v_cvt_pk_bf16_f32 v190, v192, v193
	v_cvt_pk_bf16_f32 v191, v194, v195
	ds_write_b64 v204, v[188:189] offset:16960
	ds_write_b64 v204, v[190:191] offset:17088
	global_load_dwordx4 v[128:131], v170, s[58:59] offset:192
	global_load_dwordx4 v[132:135], v170, s[58:59] offset:448
	global_load_dwordx4 v[144:147], v201, s[8:9] offset:128
	global_load_dwordx4 v[148:151], v201, s[8:9] offset:144
	global_load_dwordx4 v[152:155], v203, s[8:9] offset:128
	global_load_dwordx4 v[156:159], v203, s[8:9] offset:144
	s_waitcnt vmcnt(6)
	v_pk_mul_f32 v[180:181], v[84:85], v[196:197]
	v_pk_mul_f32 v[184:185], v[68:69], v[196:197]
	v_pk_mul_f32 v[182:183], v[86:87], v[196:197]
	v_pk_mul_f32 v[186:187], v[70:71], v[196:197]
	v_pk_mul_f32 v[180:181], v[180:181], v[136:137]
	v_pk_mul_f32 v[184:185], v[184:185], v[140:141]
	v_pk_mul_f32 v[182:183], v[182:183], v[138:139]
	v_pk_mul_f32 v[186:187], v[186:187], v[142:143]
	v_mul_f32_e32 v188, v184, v161
	v_mul_f32_e32 v192, v180, v161
	v_mul_f32_e32 v189, v185, v163
	v_mul_f32_e32 v193, v181, v163
	v_mul_f32_e32 v190, v186, v165
	v_mul_f32_e32 v194, v182, v165
	v_mul_f32_e32 v191, v187, v167
	v_mul_f32_e32 v195, v183, v167
	v_fma_f32 v188, v180, v160, -v188
	v_fma_f32 v192, v184, v160, v192
	v_fma_f32 v189, v181, v162, -v189
	v_fma_f32 v193, v185, v162, v193
	v_fma_f32 v190, v182, v164, -v190
	v_fma_f32 v194, v186, v164, v194
	v_fma_f32 v191, v183, v166, -v191
	v_fma_f32 v195, v187, v166, v195
	v_cvt_pk_bf16_f32 v188, v188, v189
	v_cvt_pk_bf16_f32 v189, v190, v191
	v_cvt_pk_bf16_f32 v190, v192, v193
	v_cvt_pk_bf16_f32 v191, v194, v195
	ds_write_b64 v204, v[188:189] offset:80
	ds_write_b64 v204, v[190:191] offset:208
	v_pk_mul_f32 v[180:181], v[20:21], v[198:199]
	v_pk_mul_f32 v[184:185], v[4:5], v[198:199]
	v_pk_mul_f32 v[182:183], v[22:23], v[198:199]
	v_pk_mul_f32 v[186:187], v[6:7], v[198:199]
	v_pk_mul_f32 v[180:181], v[180:181], v[136:137]
	v_pk_mul_f32 v[184:185], v[184:185], v[140:141]
	v_pk_mul_f32 v[182:183], v[182:183], v[138:139]
	v_pk_mul_f32 v[186:187], v[186:187], v[142:143]
	v_mul_f32_e32 v188, v184, v173
	v_mul_f32_e32 v192, v180, v173
	v_mul_f32_e32 v189, v185, v175
	v_mul_f32_e32 v193, v181, v175
	v_mul_f32_e32 v190, v186, v177
	v_mul_f32_e32 v194, v182, v177
	v_mul_f32_e32 v191, v187, v179
	v_mul_f32_e32 v195, v183, v179
	v_fma_f32 v188, v180, v172, -v188
	v_fma_f32 v192, v184, v172, v192
	v_fma_f32 v189, v181, v174, -v189
	v_fma_f32 v193, v185, v174, v193
	v_fma_f32 v190, v182, v176, -v190
	v_fma_f32 v194, v186, v176, v194
	v_fma_f32 v191, v183, v178, -v191
	v_fma_f32 v195, v187, v178, v195
	v_cvt_pk_bf16_f32 v188, v188, v189
	v_cvt_pk_bf16_f32 v189, v190, v191
	v_cvt_pk_bf16_f32 v190, v192, v193
	v_cvt_pk_bf16_f32 v191, v194, v195
	ds_write_b64 v204, v[188:189] offset:16976
	ds_write_b64 v204, v[190:191] offset:17104
	global_load_dwordx4 v[136:139], v170, s[58:59] offset:224
	global_load_dwordx4 v[140:143], v170, s[58:59] offset:480
	global_load_dwordx4 v[160:163], v201, s[8:9] offset:192
	global_load_dwordx4 v[164:167], v201, s[8:9] offset:208
	global_load_dwordx4 v[172:175], v203, s[8:9] offset:192
	global_load_dwordx4 v[176:179], v203, s[8:9] offset:208
	s_waitcnt vmcnt(6)
	v_pk_mul_f32 v[180:181], v[88:89], v[196:197]
	v_pk_mul_f32 v[184:185], v[72:73], v[196:197]
	v_pk_mul_f32 v[182:183], v[90:91], v[196:197]
	v_pk_mul_f32 v[186:187], v[74:75], v[196:197]
	v_pk_mul_f32 v[180:181], v[180:181], v[128:129]
	v_pk_mul_f32 v[184:185], v[184:185], v[132:133]
	v_pk_mul_f32 v[182:183], v[182:183], v[130:131]
	v_pk_mul_f32 v[186:187], v[186:187], v[134:135]
	v_mul_f32_e32 v188, v184, v145
	v_mul_f32_e32 v192, v180, v145
	v_mul_f32_e32 v189, v185, v147
	v_mul_f32_e32 v193, v181, v147
	v_mul_f32_e32 v190, v186, v149
	v_mul_f32_e32 v194, v182, v149
	v_mul_f32_e32 v191, v187, v151
	v_mul_f32_e32 v195, v183, v151
	v_fma_f32 v188, v180, v144, -v188
	v_fma_f32 v192, v184, v144, v192
	v_fma_f32 v189, v181, v146, -v189
	v_fma_f32 v193, v185, v146, v193
	v_fma_f32 v190, v182, v148, -v190
	v_fma_f32 v194, v186, v148, v194
	v_fma_f32 v191, v183, v150, -v191
	v_fma_f32 v195, v187, v150, v195
	v_cvt_pk_bf16_f32 v188, v188, v189
	v_cvt_pk_bf16_f32 v189, v190, v191
	v_cvt_pk_bf16_f32 v190, v192, v193
	v_cvt_pk_bf16_f32 v191, v194, v195
	ds_write_b64 v204, v[188:189] offset:96
	ds_write_b64 v204, v[190:191] offset:224
	v_pk_mul_f32 v[180:181], v[24:25], v[198:199]
	v_pk_mul_f32 v[184:185], v[8:9], v[198:199]
	v_pk_mul_f32 v[182:183], v[26:27], v[198:199]
	v_pk_mul_f32 v[186:187], v[10:11], v[198:199]
	v_pk_mul_f32 v[180:181], v[180:181], v[128:129]
	v_pk_mul_f32 v[184:185], v[184:185], v[132:133]
	v_pk_mul_f32 v[182:183], v[182:183], v[130:131]
	v_pk_mul_f32 v[186:187], v[186:187], v[134:135]
	v_mul_f32_e32 v188, v184, v153
	v_mul_f32_e32 v192, v180, v153
	v_mul_f32_e32 v189, v185, v155
	v_mul_f32_e32 v193, v181, v155
	v_mul_f32_e32 v190, v186, v157
	v_mul_f32_e32 v194, v182, v157
	v_mul_f32_e32 v191, v187, v159
	v_mul_f32_e32 v195, v183, v159
	v_fma_f32 v188, v180, v152, -v188
	v_fma_f32 v192, v184, v152, v192
	v_fma_f32 v189, v181, v154, -v189
	v_fma_f32 v193, v185, v154, v193
	v_fma_f32 v190, v182, v156, -v190
	v_fma_f32 v194, v186, v156, v194
	v_fma_f32 v191, v183, v158, -v191
	v_fma_f32 v195, v187, v158, v195
	v_cvt_pk_bf16_f32 v188, v188, v189
	v_cvt_pk_bf16_f32 v189, v190, v191
	v_cvt_pk_bf16_f32 v190, v192, v193
	v_cvt_pk_bf16_f32 v191, v194, v195
	ds_write_b64 v204, v[188:189] offset:16992
	ds_write_b64 v204, v[190:191] offset:17120
	s_waitcnt vmcnt(0)
	v_pk_mul_f32 v[180:181], v[92:93], v[196:197]
	v_pk_mul_f32 v[184:185], v[76:77], v[196:197]
	v_pk_mul_f32 v[182:183], v[94:95], v[196:197]
	v_pk_mul_f32 v[186:187], v[78:79], v[196:197]
	v_pk_mul_f32 v[180:181], v[180:181], v[136:137]
	v_pk_mul_f32 v[184:185], v[184:185], v[140:141]
	v_pk_mul_f32 v[182:183], v[182:183], v[138:139]
	v_pk_mul_f32 v[186:187], v[186:187], v[142:143]
	v_mul_f32_e32 v188, v184, v161
	v_mul_f32_e32 v192, v180, v161
	v_mul_f32_e32 v189, v185, v163
	v_mul_f32_e32 v193, v181, v163
	v_mul_f32_e32 v190, v186, v165
	v_mul_f32_e32 v194, v182, v165
	v_mul_f32_e32 v191, v187, v167
	v_mul_f32_e32 v195, v183, v167
	v_fma_f32 v188, v180, v160, -v188
	v_fma_f32 v192, v184, v160, v192
	v_fma_f32 v189, v181, v162, -v189
	v_fma_f32 v193, v185, v162, v193
	v_fma_f32 v190, v182, v164, -v190
	v_fma_f32 v194, v186, v164, v194
	v_fma_f32 v191, v183, v166, -v191
	v_fma_f32 v195, v187, v166, v195
	v_cvt_pk_bf16_f32 v188, v188, v189
	v_cvt_pk_bf16_f32 v189, v190, v191
	v_cvt_pk_bf16_f32 v190, v192, v193
	v_cvt_pk_bf16_f32 v191, v194, v195
	ds_write_b64 v204, v[188:189] offset:112
	ds_write_b64 v204, v[190:191] offset:240
	v_pk_mul_f32 v[180:181], v[28:29], v[198:199]
	v_pk_mul_f32 v[184:185], v[12:13], v[198:199]
	v_pk_mul_f32 v[182:183], v[30:31], v[198:199]
	v_pk_mul_f32 v[186:187], v[14:15], v[198:199]
	v_pk_mul_f32 v[180:181], v[180:181], v[136:137]
	v_pk_mul_f32 v[184:185], v[184:185], v[140:141]
	v_pk_mul_f32 v[182:183], v[182:183], v[138:139]
	v_pk_mul_f32 v[186:187], v[186:187], v[142:143]
	v_mul_f32_e32 v188, v184, v173
	v_mul_f32_e32 v192, v180, v173
	v_mul_f32_e32 v189, v185, v175
	v_mul_f32_e32 v193, v181, v175
	v_mul_f32_e32 v190, v186, v177
	v_mul_f32_e32 v194, v182, v177
	v_mul_f32_e32 v191, v187, v179
	v_mul_f32_e32 v195, v183, v179
	v_fma_f32 v188, v180, v172, -v188
	v_fma_f32 v192, v184, v172, v192
	v_fma_f32 v189, v181, v174, -v189
	v_fma_f32 v193, v185, v174, v193
	v_fma_f32 v190, v182, v176, -v190
	v_fma_f32 v194, v186, v176, v194
	v_fma_f32 v191, v183, v178, -v191
	v_fma_f32 v195, v187, v178, v195
	v_cvt_pk_bf16_f32 v188, v188, v189
	v_cvt_pk_bf16_f32 v189, v190, v191
	v_cvt_pk_bf16_f32 v190, v192, v193
	v_cvt_pk_bf16_f32 v191, v194, v195
	ds_write_b64 v204, v[188:189] offset:17008
	ds_write_b64 v204, v[190:191] offset:17136
	s_branch .Lqk2_flush
.Lqk2_ctx:
	global_load_dwordx4 v[128:131], v170, s[58:59] offset:0
	global_load_dwordx4 v[132:135], v170, s[58:59] offset:256
	global_load_dwordx4 v[136:139], v170, s[58:59] offset:32
	global_load_dwordx4 v[140:143], v170, s[58:59] offset:288
	s_waitcnt vmcnt(2)
	v_pk_mul_f32 v[180:181], v[112:113], v[196:197]
	v_pk_mul_f32 v[184:185], v[96:97], v[196:197]
	v_pk_mul_f32 v[182:183], v[114:115], v[196:197]
	v_pk_mul_f32 v[186:187], v[98:99], v[196:197]
	v_pk_mul_f32 v[180:181], v[180:181], v[128:129]
	v_pk_mul_f32 v[184:185], v[184:185], v[132:133]
	v_pk_mul_f32 v[182:183], v[182:183], v[130:131]
	v_pk_mul_f32 v[186:187], v[186:187], v[134:135]
	v_cvt_pk_bf16_f32 v188, v180, v181
	v_cvt_pk_bf16_f32 v189, v182, v183
	v_cvt_pk_bf16_f32 v190, v184, v185
	v_cvt_pk_bf16_f32 v191, v186, v187
	ds_write_b64 v204, v[188:189] offset:0
	ds_write_b64 v204, v[190:191] offset:128
	v_pk_mul_f32 v[180:181], v[48:49], v[198:199]
	v_pk_mul_f32 v[184:185], v[32:33], v[198:199]
	v_pk_mul_f32 v[182:183], v[50:51], v[198:199]
	v_pk_mul_f32 v[186:187], v[34:35], v[198:199]
	v_pk_mul_f32 v[180:181], v[180:181], v[128:129]
	v_pk_mul_f32 v[184:185], v[184:185], v[132:133]
	v_pk_mul_f32 v[182:183], v[182:183], v[130:131]
	v_pk_mul_f32 v[186:187], v[186:187], v[134:135]
	v_cvt_pk_bf16_f32 v188, v180, v181
	v_cvt_pk_bf16_f32 v189, v182, v183
	v_cvt_pk_bf16_f32 v190, v184, v185
	v_cvt_pk_bf16_f32 v191, v186, v187
	ds_write_b64 v204, v[188:189] offset:16896
	ds_write_b64 v204, v[190:191] offset:17024
	global_load_dwordx4 v[128:131], v170, s[58:59] offset:64
	global_load_dwordx4 v[132:135], v170, s[58:59] offset:320
	s_waitcnt vmcnt(2)
	v_pk_mul_f32 v[180:181], v[116:117], v[196:197]
	v_pk_mul_f32 v[184:185], v[100:101], v[196:197]
	v_pk_mul_f32 v[182:183], v[118:119], v[196:197]
	v_pk_mul_f32 v[186:187], v[102:103], v[196:197]
	v_pk_mul_f32 v[180:181], v[180:181], v[136:137]
	v_pk_mul_f32 v[184:185], v[184:185], v[140:141]
	v_pk_mul_f32 v[182:183], v[182:183], v[138:139]
	v_pk_mul_f32 v[186:187], v[186:187], v[142:143]
	v_cvt_pk_bf16_f32 v188, v180, v181
	v_cvt_pk_bf16_f32 v189, v182, v183
	v_cvt_pk_bf16_f32 v190, v184, v185
	v_cvt_pk_bf16_f32 v191, v186, v187
	ds_write_b64 v204, v[188:189] offset:16
	ds_write_b64 v204, v[190:191] offset:144
	v_pk_mul_f32 v[180:181], v[52:53], v[198:199]
	v_pk_mul_f32 v[184:185], v[36:37], v[198:199]
	v_pk_mul_f32 v[182:183], v[54:55], v[198:199]
	v_pk_mul_f32 v[186:187], v[38:39], v[198:199]
	v_pk_mul_f32 v[180:181], v[180:181], v[136:137]
	v_pk_mul_f32 v[184:185], v[184:185], v[140:141]
	v_pk_mul_f32 v[182:183], v[182:183], v[138:139]
	v_pk_mul_f32 v[186:187], v[186:187], v[142:143]
	v_cvt_pk_bf16_f32 v188, v180, v181
	v_cvt_pk_bf16_f32 v189, v182, v183
	v_cvt_pk_bf16_f32 v190, v184, v185
	v_cvt_pk_bf16_f32 v191, v186, v187
	ds_write_b64 v204, v[188:189] offset:16912
	ds_write_b64 v204, v[190:191] offset:17040
	global_load_dwordx4 v[136:139], v170, s[58:59] offset:96
	global_load_dwordx4 v[140:143], v170, s[58:59] offset:352
	s_waitcnt vmcnt(2)
	v_pk_mul_f32 v[180:181], v[120:121], v[196:197]
	v_pk_mul_f32 v[184:185], v[104:105], v[196:197]
	v_pk_mul_f32 v[182:183], v[122:123], v[196:197]
	v_pk_mul_f32 v[186:187], v[106:107], v[196:197]
	v_pk_mul_f32 v[180:181], v[180:181], v[128:129]
	v_pk_mul_f32 v[184:185], v[184:185], v[132:133]
	v_pk_mul_f32 v[182:183], v[182:183], v[130:131]
	v_pk_mul_f32 v[186:187], v[186:187], v[134:135]
	v_cvt_pk_bf16_f32 v188, v180, v181
	v_cvt_pk_bf16_f32 v189, v182, v183
	v_cvt_pk_bf16_f32 v190, v184, v185
	v_cvt_pk_bf16_f32 v191, v186, v187
	ds_write_b64 v204, v[188:189] offset:32
	ds_write_b64 v204, v[190:191] offset:160
	v_pk_mul_f32 v[180:181], v[56:57], v[198:199]
	v_pk_mul_f32 v[184:185], v[40:41], v[198:199]
	v_pk_mul_f32 v[182:183], v[58:59], v[198:199]
	v_pk_mul_f32 v[186:187], v[42:43], v[198:199]
	v_pk_mul_f32 v[180:181], v[180:181], v[128:129]
	v_pk_mul_f32 v[184:185], v[184:185], v[132:133]
	v_pk_mul_f32 v[182:183], v[182:183], v[130:131]
	v_pk_mul_f32 v[186:187], v[186:187], v[134:135]
	v_cvt_pk_bf16_f32 v188, v180, v181
	v_cvt_pk_bf16_f32 v189, v182, v183
	v_cvt_pk_bf16_f32 v190, v184, v185
	v_cvt_pk_bf16_f32 v191, v186, v187
	ds_write_b64 v204, v[188:189] offset:16928
	ds_write_b64 v204, v[190:191] offset:17056
	global_load_dwordx4 v[128:131], v170, s[58:59] offset:128
	global_load_dwordx4 v[132:135], v170, s[58:59] offset:384
	s_waitcnt vmcnt(2)
	v_pk_mul_f32 v[180:181], v[124:125], v[196:197]
	v_pk_mul_f32 v[184:185], v[108:109], v[196:197]
	v_pk_mul_f32 v[182:183], v[126:127], v[196:197]
	v_pk_mul_f32 v[186:187], v[110:111], v[196:197]
	v_pk_mul_f32 v[180:181], v[180:181], v[136:137]
	v_pk_mul_f32 v[184:185], v[184:185], v[140:141]
	v_pk_mul_f32 v[182:183], v[182:183], v[138:139]
	v_pk_mul_f32 v[186:187], v[186:187], v[142:143]
	v_cvt_pk_bf16_f32 v188, v180, v181
	v_cvt_pk_bf16_f32 v189, v182, v183
	v_cvt_pk_bf16_f32 v190, v184, v185
	v_cvt_pk_bf16_f32 v191, v186, v187
	ds_write_b64 v204, v[188:189] offset:48
	ds_write_b64 v204, v[190:191] offset:176
	v_pk_mul_f32 v[180:181], v[60:61], v[198:199]
	v_pk_mul_f32 v[184:185], v[44:45], v[198:199]
	v_pk_mul_f32 v[182:183], v[62:63], v[198:199]
	v_pk_mul_f32 v[186:187], v[46:47], v[198:199]
	v_pk_mul_f32 v[180:181], v[180:181], v[136:137]
	v_pk_mul_f32 v[184:185], v[184:185], v[140:141]
	v_pk_mul_f32 v[182:183], v[182:183], v[138:139]
	v_pk_mul_f32 v[186:187], v[186:187], v[142:143]
	v_cvt_pk_bf16_f32 v188, v180, v181
	v_cvt_pk_bf16_f32 v189, v182, v183
	v_cvt_pk_bf16_f32 v190, v184, v185
	v_cvt_pk_bf16_f32 v191, v186, v187
	ds_write_b64 v204, v[188:189] offset:16944
	ds_write_b64 v204, v[190:191] offset:17072
	global_load_dwordx4 v[136:139], v170, s[58:59] offset:160
	global_load_dwordx4 v[140:143], v170, s[58:59] offset:416
	s_waitcnt vmcnt(2)
	v_pk_mul_f32 v[180:181], v[80:81], v[196:197]
	v_pk_mul_f32 v[184:185], v[64:65], v[196:197]
	v_pk_mul_f32 v[182:183], v[82:83], v[196:197]
	v_pk_mul_f32 v[186:187], v[66:67], v[196:197]
	v_pk_mul_f32 v[180:181], v[180:181], v[128:129]
	v_pk_mul_f32 v[184:185], v[184:185], v[132:133]
	v_pk_mul_f32 v[182:183], v[182:183], v[130:131]
	v_pk_mul_f32 v[186:187], v[186:187], v[134:135]
	v_cvt_pk_bf16_f32 v188, v180, v181
	v_cvt_pk_bf16_f32 v189, v182, v183
	v_cvt_pk_bf16_f32 v190, v184, v185
	v_cvt_pk_bf16_f32 v191, v186, v187
	ds_write_b64 v204, v[188:189] offset:64
	ds_write_b64 v204, v[190:191] offset:192
	v_pk_mul_f32 v[180:181], v[16:17], v[198:199]
	v_pk_mul_f32 v[184:185], v[0:1], v[198:199]
	v_pk_mul_f32 v[182:183], v[18:19], v[198:199]
	v_pk_mul_f32 v[186:187], v[2:3], v[198:199]
	v_pk_mul_f32 v[180:181], v[180:181], v[128:129]
	v_pk_mul_f32 v[184:185], v[184:185], v[132:133]
	v_pk_mul_f32 v[182:183], v[182:183], v[130:131]
	v_pk_mul_f32 v[186:187], v[186:187], v[134:135]
	v_cvt_pk_bf16_f32 v188, v180, v181
	v_cvt_pk_bf16_f32 v189, v182, v183
	v_cvt_pk_bf16_f32 v190, v184, v185
	v_cvt_pk_bf16_f32 v191, v186, v187
	ds_write_b64 v204, v[188:189] offset:16960
	ds_write_b64 v204, v[190:191] offset:17088
	global_load_dwordx4 v[128:131], v170, s[58:59] offset:192
	global_load_dwordx4 v[132:135], v170, s[58:59] offset:448
	s_waitcnt vmcnt(2)
	v_pk_mul_f32 v[180:181], v[84:85], v[196:197]
	v_pk_mul_f32 v[184:185], v[68:69], v[196:197]
	v_pk_mul_f32 v[182:183], v[86:87], v[196:197]
	v_pk_mul_f32 v[186:187], v[70:71], v[196:197]
	v_pk_mul_f32 v[180:181], v[180:181], v[136:137]
	v_pk_mul_f32 v[184:185], v[184:185], v[140:141]
	v_pk_mul_f32 v[182:183], v[182:183], v[138:139]
	v_pk_mul_f32 v[186:187], v[186:187], v[142:143]
	v_cvt_pk_bf16_f32 v188, v180, v181
	v_cvt_pk_bf16_f32 v189, v182, v183
	v_cvt_pk_bf16_f32 v190, v184, v185
	v_cvt_pk_bf16_f32 v191, v186, v187
	ds_write_b64 v204, v[188:189] offset:80
	ds_write_b64 v204, v[190:191] offset:208
	v_pk_mul_f32 v[180:181], v[20:21], v[198:199]
	v_pk_mul_f32 v[184:185], v[4:5], v[198:199]
	v_pk_mul_f32 v[182:183], v[22:23], v[198:199]
	v_pk_mul_f32 v[186:187], v[6:7], v[198:199]
	v_pk_mul_f32 v[180:181], v[180:181], v[136:137]
	v_pk_mul_f32 v[184:185], v[184:185], v[140:141]
	v_pk_mul_f32 v[182:183], v[182:183], v[138:139]
	v_pk_mul_f32 v[186:187], v[186:187], v[142:143]
	v_cvt_pk_bf16_f32 v188, v180, v181
	v_cvt_pk_bf16_f32 v189, v182, v183
	v_cvt_pk_bf16_f32 v190, v184, v185
	v_cvt_pk_bf16_f32 v191, v186, v187
	ds_write_b64 v204, v[188:189] offset:16976
	ds_write_b64 v204, v[190:191] offset:17104
	global_load_dwordx4 v[136:139], v170, s[58:59] offset:224
	global_load_dwordx4 v[140:143], v170, s[58:59] offset:480
	s_waitcnt vmcnt(2)
	v_pk_mul_f32 v[180:181], v[88:89], v[196:197]
	v_pk_mul_f32 v[184:185], v[72:73], v[196:197]
	v_pk_mul_f32 v[182:183], v[90:91], v[196:197]
	v_pk_mul_f32 v[186:187], v[74:75], v[196:197]
	v_pk_mul_f32 v[180:181], v[180:181], v[128:129]
	v_pk_mul_f32 v[184:185], v[184:185], v[132:133]
	v_pk_mul_f32 v[182:183], v[182:183], v[130:131]
	v_pk_mul_f32 v[186:187], v[186:187], v[134:135]
	v_cvt_pk_bf16_f32 v188, v180, v181
	v_cvt_pk_bf16_f32 v189, v182, v183
	v_cvt_pk_bf16_f32 v190, v184, v185
	v_cvt_pk_bf16_f32 v191, v186, v187
	ds_write_b64 v204, v[188:189] offset:96
	ds_write_b64 v204, v[190:191] offset:224
	v_pk_mul_f32 v[180:181], v[24:25], v[198:199]
	v_pk_mul_f32 v[184:185], v[8:9], v[198:199]
	v_pk_mul_f32 v[182:183], v[26:27], v[198:199]
	v_pk_mul_f32 v[186:187], v[10:11], v[198:199]
	v_pk_mul_f32 v[180:181], v[180:181], v[128:129]
	v_pk_mul_f32 v[184:185], v[184:185], v[132:133]
	v_pk_mul_f32 v[182:183], v[182:183], v[130:131]
	v_pk_mul_f32 v[186:187], v[186:187], v[134:135]
	v_cvt_pk_bf16_f32 v188, v180, v181
	v_cvt_pk_bf16_f32 v189, v182, v183
	v_cvt_pk_bf16_f32 v190, v184, v185
	v_cvt_pk_bf16_f32 v191, v186, v187
	ds_write_b64 v204, v[188:189] offset:16992
	ds_write_b64 v204, v[190:191] offset:17120
	s_waitcnt vmcnt(0)
	v_pk_mul_f32 v[180:181], v[92:93], v[196:197]
	v_pk_mul_f32 v[184:185], v[76:77], v[196:197]
	v_pk_mul_f32 v[182:183], v[94:95], v[196:197]
	v_pk_mul_f32 v[186:187], v[78:79], v[196:197]
	v_pk_mul_f32 v[180:181], v[180:181], v[136:137]
	v_pk_mul_f32 v[184:185], v[184:185], v[140:141]
	v_pk_mul_f32 v[182:183], v[182:183], v[138:139]
	v_pk_mul_f32 v[186:187], v[186:187], v[142:143]
	v_cvt_pk_bf16_f32 v188, v180, v181
	v_cvt_pk_bf16_f32 v189, v182, v183
	v_cvt_pk_bf16_f32 v190, v184, v185
	v_cvt_pk_bf16_f32 v191, v186, v187
	ds_write_b64 v204, v[188:189] offset:112
	ds_write_b64 v204, v[190:191] offset:240
	v_pk_mul_f32 v[180:181], v[28:29], v[198:199]
	v_pk_mul_f32 v[184:185], v[12:13], v[198:199]
	v_pk_mul_f32 v[182:183], v[30:31], v[198:199]
	v_pk_mul_f32 v[186:187], v[14:15], v[198:199]
	v_pk_mul_f32 v[180:181], v[180:181], v[136:137]
	v_pk_mul_f32 v[184:185], v[184:185], v[140:141]
	v_pk_mul_f32 v[182:183], v[182:183], v[138:139]
	v_pk_mul_f32 v[186:187], v[186:187], v[142:143]
	v_cvt_pk_bf16_f32 v188, v180, v181
	v_cvt_pk_bf16_f32 v189, v182, v183
	v_cvt_pk_bf16_f32 v190, v184, v185
	v_cvt_pk_bf16_f32 v191, v186, v187
	ds_write_b64 v204, v[188:189] offset:17008
	ds_write_b64 v204, v[190:191] offset:17136
.Lqk2_flush:
	s_ashr_i32 s35, s34, 3
	s_cmp_eq_u32 s36, 4
	s_cbranch_scc1 .Lqk2_k
	s_lshl_b32 s55, s35, 11
	s_or_b32 s55, s55, s12
	s_lshl_b32 s99, s36, 9
	s_mul_hi_u32 s57, s55, 0x800
	s_mul_i32 s56, s55, 0x800
	s_add_u32 s56, s56, s99
	s_addc_u32 s57, s57, 0
	s_add_u32 s56, s56, s22
	s_addc_u32 s57, s57, s23
	v_lshrrev_b32_e32 v229, 5, v208
	v_mul_u32_u24_e32 v229, 0x800, v229
	v_add_u32_e32 v207, v207, v229
	s_waitcnt lgkmcnt(0)
	s_barrier
	ds_read_b128 v[128:131], v205 offset:0
	ds_read_b128 v[132:135], v205 offset:8448
	ds_read_b128 v[136:139], v205 offset:16896
	ds_read_b128 v[140:143], v205 offset:25344
	ds_read_b128 v[144:147], v205 offset:33792
	ds_read_b128 v[148:151], v205 offset:42240
	ds_read_b128 v[152:155], v205 offset:50688
	ds_read_b128 v[156:159], v205 offset:59136
	ds_read_b128 v[160:163], v206 offset:0
	ds_read_b128 v[164:167], v206 offset:8448
	ds_read_b128 v[172:175], v206 offset:16896
	ds_read_b128 v[176:179], v206 offset:25344
	ds_read_b128 v[180:183], v206 offset:33792
	ds_read_b128 v[184:187], v206 offset:42240
	ds_read_b128 v[188:191], v206 offset:50688
	ds_read_b128 v[192:195], v206 offset:59136
	s_waitcnt lgkmcnt(15)
	global_store_dwordx4 v207, v[128:131], s[56:57]
	s_add_u32 s56, s56, 0x8000
	s_addc_u32 s57, s57, 0
	s_waitcnt lgkmcnt(14)
	global_store_dwordx4 v207, v[132:135], s[56:57]
	s_add_u32 s56, s56, 0x8000
	s_addc_u32 s57, s57, 0
	s_waitcnt lgkmcnt(13)
	global_store_dwordx4 v207, v[136:139], s[56:57]
	s_add_u32 s56, s56, 0x8000
	s_addc_u32 s57, s57, 0
	s_waitcnt lgkmcnt(12)
	global_store_dwordx4 v207, v[140:143], s[56:57]
	s_add_u32 s56, s56, 0x8000
	s_addc_u32 s57, s57, 0
	s_waitcnt lgkmcnt(11)
	global_store_dwordx4 v207, v[144:147], s[56:57]
	s_add_u32 s56, s56, 0x8000
	s_addc_u32 s57, s57, 0
	s_waitcnt lgkmcnt(10)
	global_store_dwordx4 v207, v[148:151], s[56:57]
	s_add_u32 s56, s56, 0x8000
	s_addc_u32 s57, s57, 0
	s_waitcnt lgkmcnt(9)
	global_store_dwordx4 v207, v[152:155], s[56:57]
	s_add_u32 s56, s56, 0x8000
	s_addc_u32 s57, s57, 0
	s_waitcnt lgkmcnt(8)
	global_store_dwordx4 v207, v[156:159], s[56:57]
	s_add_u32 s56, s56, 0x8000
	s_addc_u32 s57, s57, 0
	s_waitcnt lgkmcnt(7)
	global_store_dwordx4 v207, v[160:163], s[56:57]
	s_add_u32 s56, s56, 0x8000
	s_addc_u32 s57, s57, 0
	s_waitcnt lgkmcnt(6)
	global_store_dwordx4 v207, v[164:167], s[56:57]
	s_add_u32 s56, s56, 0x8000
	s_addc_u32 s57, s57, 0
	s_waitcnt lgkmcnt(5)
	global_store_dwordx4 v207, v[172:175], s[56:57]
	s_add_u32 s56, s56, 0x8000
	s_addc_u32 s57, s57, 0
	s_waitcnt lgkmcnt(4)
	global_store_dwordx4 v207, v[176:179], s[56:57]
	s_add_u32 s56, s56, 0x8000
	s_addc_u32 s57, s57, 0
	s_waitcnt lgkmcnt(3)
	global_store_dwordx4 v207, v[180:183], s[56:57]
	s_add_u32 s56, s56, 0x8000
	s_addc_u32 s57, s57, 0
	s_waitcnt lgkmcnt(2)
	global_store_dwordx4 v207, v[184:187], s[56:57]
	s_add_u32 s56, s56, 0x8000
	s_addc_u32 s57, s57, 0
	s_waitcnt lgkmcnt(1)
	global_store_dwordx4 v207, v[188:191], s[56:57]
	s_add_u32 s56, s56, 0x8000
	s_addc_u32 s57, s57, 0
	s_waitcnt lgkmcnt(0)
	global_store_dwordx4 v207, v[192:195], s[56:57]
	s_barrier
	s_branch .LBB0_219
.Lqk2_k:
	s_cmpk_gt_i32 s42, 0xaff
	s_cbranch_scc1 .Lqk2_kc
	s_mul_i32 s55, s35, 0x900
	s_add_u32 s55, s55, s12
	s_add_u32 s55, s55, 0x100
	s_branch .Lqk2_kd
.Lqk2_kc:
	s_mul_i32 s55, s34, 0x900
.Lqk2_kd:
	s_mul_hi_u32 s57, s55, 0x200
	s_mul_i32 s56, s55, 0x200
	s_add_u32 s56, s56, s24
	s_addc_u32 s57, s57, s25
	v_lshrrev_b32_e32 v229, 5, v208
	v_mul_u32_u24_e32 v229, 0x200, v229
	v_add_u32_e32 v207, v207, v229
	s_waitcnt lgkmcnt(0)
	s_barrier
	ds_read_b128 v[128:131], v205 offset:0
	ds_read_b128 v[132:135], v205 offset:8448
	ds_read_b128 v[136:139], v205 offset:16896
	ds_read_b128 v[140:143], v205 offset:25344
	ds_read_b128 v[144:147], v205 offset:33792
	ds_read_b128 v[148:151], v205 offset:42240
	ds_read_b128 v[152:155], v205 offset:50688
	ds_read_b128 v[156:159], v205 offset:59136
	ds_read_b128 v[160:163], v206 offset:0
	ds_read_b128 v[164:167], v206 offset:8448
	ds_read_b128 v[172:175], v206 offset:16896
	ds_read_b128 v[176:179], v206 offset:25344
	ds_read_b128 v[180:183], v206 offset:33792
	ds_read_b128 v[184:187], v206 offset:42240
	ds_read_b128 v[188:191], v206 offset:50688
	ds_read_b128 v[192:195], v206 offset:59136
	s_waitcnt lgkmcnt(15)
	global_store_dwordx4 v207, v[128:131], s[56:57]
	s_add_u32 s56, s56, 0x2000
	s_addc_u32 s57, s57, 0
	s_waitcnt lgkmcnt(14)
	global_store_dwordx4 v207, v[132:135], s[56:57]
	s_add_u32 s56, s56, 0x2000
	s_addc_u32 s57, s57, 0
	s_waitcnt lgkmcnt(13)
	global_store_dwordx4 v207, v[136:139], s[56:57]
	s_add_u32 s56, s56, 0x2000
	s_addc_u32 s57, s57, 0
	s_waitcnt lgkmcnt(12)
	global_store_dwordx4 v207, v[140:143], s[56:57]
	s_add_u32 s56, s56, 0x2000
	s_addc_u32 s57, s57, 0
	s_waitcnt lgkmcnt(11)
	global_store_dwordx4 v207, v[144:147], s[56:57]
	s_add_u32 s56, s56, 0x2000
	s_addc_u32 s57, s57, 0
	s_waitcnt lgkmcnt(10)
	global_store_dwordx4 v207, v[148:151], s[56:57]
	s_add_u32 s56, s56, 0x2000
	s_addc_u32 s57, s57, 0
	s_waitcnt lgkmcnt(9)
	global_store_dwordx4 v207, v[152:155], s[56:57]
	s_add_u32 s56, s56, 0x2000
	s_addc_u32 s57, s57, 0
	s_waitcnt lgkmcnt(8)
	global_store_dwordx4 v207, v[156:159], s[56:57]
	s_add_u32 s56, s56, 0x2000
	s_addc_u32 s57, s57, 0
	s_waitcnt lgkmcnt(7)
	global_store_dwordx4 v207, v[160:163], s[56:57]
	s_add_u32 s56, s56, 0x2000
	s_addc_u32 s57, s57, 0
	s_waitcnt lgkmcnt(6)
	global_store_dwordx4 v207, v[164:167], s[56:57]
	s_add_u32 s56, s56, 0x2000
	s_addc_u32 s57, s57, 0
	s_waitcnt lgkmcnt(5)
	global_store_dwordx4 v207, v[172:175], s[56:57]
	s_add_u32 s56, s56, 0x2000
	s_addc_u32 s57, s57, 0
	s_waitcnt lgkmcnt(4)
	global_store_dwordx4 v207, v[176:179], s[56:57]
	s_add_u32 s56, s56, 0x2000
	s_addc_u32 s57, s57, 0
	s_waitcnt lgkmcnt(3)
	global_store_dwordx4 v207, v[180:183], s[56:57]
	s_add_u32 s56, s56, 0x2000
	s_addc_u32 s57, s57, 0
	s_waitcnt lgkmcnt(2)
	global_store_dwordx4 v207, v[184:187], s[56:57]
	s_add_u32 s56, s56, 0x2000
	s_addc_u32 s57, s57, 0
	s_waitcnt lgkmcnt(1)
	global_store_dwordx4 v207, v[188:191], s[56:57]
	s_add_u32 s56, s56, 0x2000
	s_addc_u32 s57, s57, 0
	s_waitcnt lgkmcnt(0)
	global_store_dwordx4 v207, v[192:195], s[56:57]
	s_barrier
	s_branch .LBB0_219
